# same as previous best; the LDS table tag starts from a value no table address can take
# speedup vs baseline: 1.0007x; 1.0007x over previous
; #define TIDX tid_opaque()
; DI void row2_phase(const Params& P, int l, int r_begin, char* smem) {
;   const int tid = TIDX, lane = tid & 63, wave = tid >> 6, fr = lane & 15, fq = lane >> 4;
;   float* lg = (float*)smem + wave * 16 * 48;
;   const half_t* Whi = P.WrH + (size_t)(l * 2) * 49152; const half_t* Wlo = Whi + 49152;
;   const int ngroups = (TA - r_begin) >> 4, gw = blockIdx.x * 4 + wave, nw = gridDim.x * 4;
;   const float* gam = P.norm2_g + l * 1024;
;   const int gper = (ngroups + nw - 1) / nw;
; #pragma unroll 1
;   for (int grp = gw * gper; grp < min((gw + 1) * gper, ngroups); grp++) {
.LBB0_542:
	s_or_b64 exec, exec, s[0:1]
	v_readlane_b32 s0, v255, 48
	v_readlane_b32 s1, v255, 49
	s_and_b64 s[0:1], s[0:1], exec
	s_cselect_b32 s22, 0, 0x800
	v_mov_b32_e32 v1, v172
	s_lshr_b32 s0, s22, 4
	s_barrier
	s_mov_b32 s44, 1
	v_accvgpr_write_b32 a255, v104
	v_and_b32_e32 v104, 0xff, v172
	v_lshlrev_b32_e32 v104, 4, v104
	v_add_u32_e32 v104, 0x4000, v104
	ds_write_b128 v104, v[84:87] offset:0
	ds_write_b128 v104, v[88:91] offset:4096
	ds_write_b128 v104, v[92:95] offset:8192
	ds_write_b128 v104, v[96:99] offset:12288
	ds_write_b128 v104, v[100:103] offset:16384
	s_waitcnt lgkmcnt(0)
	v_accvgpr_read_b32 v104, a255
	v_mov_b32_e32 v84, 0
	v_lshlrev_b32_e32 v85, 2, v172
	v_add_u32_e32 v85, 0x3000, v85
	ds_write_b32 v85, v84
	s_waitcnt lgkmcnt(0)
	s_barrier
	s_xor_b32 s1, s0, 0x1080
	v_ashrrev_i32_e32 v2, 6, v1
	v_readlane_b32 s0, v254, 20
	v_readlane_b32 s3, v254, 22
	v_readlane_b32 s6, v254, 25
	v_add_u32_e32 v0, s0, v2
	v_readlane_b32 s0, v254, 21
	s_add_i32 s0, s0, s1
	s_ashr_i32 s2, s0, 31
	s_xor_b32 s2, s2, s3
	s_abs_i32 s0, s0
	v_readlane_b32 s3, v254, 26
	s_mul_hi_u32 s3, s0, s3
	s_mul_i32 s4, s3, s6
	s_sub_i32 s0, s0, s4
	s_add_i32 s4, s3, 1
	s_sub_i32 s5, s0, s6
	s_cmp_ge_u32 s0, s6
	s_cselect_b32 s3, s4, s3
	s_cselect_b32 s0, s5, s0
	s_add_i32 s4, s3, 1
	s_cmp_ge_u32 s0, s6
	s_cselect_b32 s0, s4, s3
	s_xor_b32 s0, s0, s2
	s_sub_i32 s0, s0, s2
	v_mul_lo_u32 v17, v0, s0
	v_add_u32_e32 v3, s0, v17
	v_min_i32_e32 v52, s1, v3
	v_cmp_lt_i32_e32 vcc, v17, v52
	s_and_saveexec_b64 s[10:11], vcc
	s_cbranch_execz .LBB0_551
	v_readlane_b32 s2, v254, 39
	v_readlane_b32 s48, v255, 3
	v_readlane_b32 s3, v254, 40
	v_readlane_b32 s56, v255, 11
	v_readlane_b32 s57, v255, 12
	v_readlane_b32 s58, v255, 13
	v_readlane_b32 s59, v255, 14
	v_readlane_b32 s60, v255, 15
	v_readlane_b32 s61, v255, 16
	s_mov_b32 s3, s85
	v_readlane_b32 s62, v255, 17
	v_readlane_b32 s63, v255, 18
	s_mov_b64 s[56:57], s[60:61]
	s_lshl_b64 s[2:3], s[2:3], 2
	s_mov_b64 s[58:59], s[62:63]
	v_readlane_b32 s49, v255, 4
	v_readlane_b32 s50, v255, 5
	v_readlane_b32 s51, v255, 6
	v_readlane_b32 s52, v255, 7
	v_readlane_b32 s53, v255, 8
	v_readlane_b32 s54, v255, 9
	v_readlane_b32 s55, v255, 10
	s_add_u32 s2, s58, s2
	s_addc_u32 s3, s59, s3
	s_movk_i32 s1, 0xc00
	v_bfe_u32 v4, v1, 4, 2
	v_readlane_b32 s4, v255, 26
	v_readlane_b32 s48, v253, 35
	v_and_b32_e32 v53, 63, v1
	v_and_b32_e32 v54, 15, v1
	v_mul_lo_u32 v3, v2, s1
	v_lshlrev_b32_e32 v12, 5, v4
	v_mov_b32_e32 v13, v149
	s_movk_i32 s1, 0xc0
	s_lshl_b32 s23, s4, 5
	v_readlane_b32 s50, v253, 37
	v_readlane_b32 s6, v254, 41
	v_mul_lo_u32 v0, v0, s0
	v_lshlrev_b32_e32 v2, 3, v4
	v_lshl_add_u64 v[14:15], s[2:3], 0, v[12:13]
	v_lshl_or_b32 v5, v54, 2, v3
	v_mad_u32_u24 v13, v53, s1, v3
	v_mul_u32_u24_e32 v3, 0x300, v4
	v_readlane_b32 s51, v253, 38
	v_readlane_b32 s7, v254, 42
	s_add_u32 s8, s50, s6
	s_mul_hi_u32 s1, s4, 0x30000
	s_mul_i32 s4, s4, 0x30000
	v_lshlrev_b32_e32 v4, 11, v54
	v_and_b32_e32 v16, 48, v1
	v_lshlrev_b32_e32 v0, 4, v0
	v_cmp_gt_u32_e64 s[2:3], 16, v53
	s_addc_u32 s9, s51, s7
	v_or3_b32 v18, s4, v4, v16
	v_mov_b32_e32 v19, s1
	v_add3_u32 v20, s22, v0, v54
	s_mov_b64 s[20:21], 0
	v_lshlrev_b32_e32 v148, 2, v2
	v_add_u32_e32 v55, v5, v3
	v_readlane_b32 s5, v255, 27
	v_readlane_b32 s49, v253, 36
	v_readlane_b32 s52, v253, 39
	v_readlane_b32 s53, v253, 40
	v_readlane_b32 s54, v253, 41
	v_readlane_b32 s55, v253, 42
	v_readlane_b32 s56, v253, 43
	v_readlane_b32 s57, v253, 44
	v_readlane_b32 s58, v253, 45
	v_readlane_b32 s59, v253, 46
	v_readlane_b32 s60, v253, 47
	v_readlane_b32 s61, v253, 48
	v_readlane_b32 s62, v253, 49
	v_readlane_b32 s63, v253, 50
	s_branch .LBB0_545
